# grid barrier: XCD leader publishes the generation before its own acquire invalidate
# baseline (speedup 1.0000x reference)
; __device__ __forceinline__ unsigned xb_ld(unsigned* p)              { return __hip_atomic_load(p, __ATOMIC_RELAXED, __HIP_MEMORY_SCOPE_AGENT); }
; __device__ __forceinline__ unsigned xb_add(unsigned* p, unsigned v) { return __hip_atomic_fetch_add(p, v, __ATOMIC_RELAXED, __HIP_MEMORY_SCOPE_AGENT); }
; #define XB_SPIN(cond, bar) do { unsigned _sp = 0; while (cond) { __builtin_amdgcn_s_sleep(1); \
;     if ((++_sp & 255u) == 0u) { if (xb_ld(&(bar)[XB_TMO])) break; if (_sp > XB_SPIN_CAP) { atomicAdd(&(bar)[XB_TMO], 1u); break; } } } } while (0)
; __device__ __forceinline__ void xcd_barrier(const XcdBarrier& b) {
;     ...
;             const unsigned og = xb_add(&bar[XB_TOP], 1u);
;             const unsigned tg = og / nx;
;             if (og + 1u == (tg + 1u) * nx) xb_add(&bar[XB_TOPGEN], 1u);
;             else XB_SPIN(xb_ld(&bar[XB_TOPGEN]) == tg, bar);
;             __builtin_amdgcn_fence(__ATOMIC_ACQUIRE, "agent");
;             xb_add(&bar[XB_XGEN(b.x)], 1u);
;             asm volatile("s_waitcnt vmcnt(0)" ::: "memory");
.LBB0_137:
	s_or_b64 exec, exec, s[6:7]
	s_mov_b64 s[6:7], exec
	v_mbcnt_lo_u32_b32 v0, s6, 0
	v_mbcnt_hi_u32_b32 v0, s7, v0
	v_cmp_eq_u32_e32 vcc, 0, v0
	s_waitcnt vmcnt(0)
	s_and_saveexec_b64 s[8:9], vcc
	s_cbranch_execz .LBB0_139
	s_bcnt1_i32_b64 s3, s[6:7]
	v_mov_b32_e32 v0, 0x2000
	v_mov_b32_e32 v1, s3
	global_atomic_add v0, v1, s[4:5] offset:1024
.LBB0_139:
	s_or_b64 exec, exec, s[8:9]
	buffer_inv sc1
	s_waitcnt vmcnt(0)

; __device__ __forceinline__ unsigned xb_ld(unsigned* p)              { return __hip_atomic_load(p, __ATOMIC_RELAXED, __HIP_MEMORY_SCOPE_AGENT); }
; __device__ __forceinline__ unsigned xb_add(unsigned* p, unsigned v) { return __hip_atomic_fetch_add(p, v, __ATOMIC_RELAXED, __HIP_MEMORY_SCOPE_AGENT); }
; #define XB_SPIN(cond, bar) do { unsigned _sp = 0; while (cond) { __builtin_amdgcn_s_sleep(1); \
;     if ((++_sp & 255u) == 0u) { if (xb_ld(&(bar)[XB_TMO])) break; if (_sp > XB_SPIN_CAP) { atomicAdd(&(bar)[XB_TMO], 1u); break; } } } } while (0)
; __device__ __forceinline__ void xcd_barrier(const XcdBarrier& b) {
;     ...
;             const unsigned og = xb_add(&bar[XB_TOP], 1u);
;             const unsigned tg = og / nx;
;             if (og + 1u == (tg + 1u) * nx) xb_add(&bar[XB_TOPGEN], 1u);
;             else XB_SPIN(xb_ld(&bar[XB_TOPGEN]) == tg, bar);
;             __builtin_amdgcn_fence(__ATOMIC_ACQUIRE, "agent");
;             xb_add(&bar[XB_XGEN(b.x)], 1u);
;             asm volatile("s_waitcnt vmcnt(0)" ::: "memory");
.LBB0_199:
	s_or_b64 exec, exec, s[8:9]
	s_mov_b64 s[8:9], exec
	v_mbcnt_lo_u32_b32 v0, s8, 0
	v_mbcnt_hi_u32_b32 v0, s9, v0
	v_cmp_eq_u32_e32 vcc, 0, v0
	s_waitcnt vmcnt(0)
	s_and_saveexec_b64 s[10:11], vcc
	s_cbranch_execz .LBB0_201
	s_bcnt1_i32_b64 s3, s[8:9]
	v_mov_b32_e32 v0, 0x2000
	v_mov_b32_e32 v1, s3
	global_atomic_add v0, v1, s[4:5] offset:1024
.LBB0_201:
	s_or_b64 exec, exec, s[10:11]
	buffer_inv sc1
	s_waitcnt vmcnt(0)

; __device__ __forceinline__ unsigned xb_ld(unsigned* p)              { return __hip_atomic_load(p, __ATOMIC_RELAXED, __HIP_MEMORY_SCOPE_AGENT); }
; __device__ __forceinline__ unsigned xb_add(unsigned* p, unsigned v) { return __hip_atomic_fetch_add(p, v, __ATOMIC_RELAXED, __HIP_MEMORY_SCOPE_AGENT); }
; #define XB_SPIN(cond, bar) do { unsigned _sp = 0; while (cond) { __builtin_amdgcn_s_sleep(1); \
;     if ((++_sp & 255u) == 0u) { if (xb_ld(&(bar)[XB_TMO])) break; if (_sp > XB_SPIN_CAP) { atomicAdd(&(bar)[XB_TMO], 1u); break; } } } } while (0)
; __device__ __forceinline__ void xcd_barrier(const XcdBarrier& b) {
;     ...
;             const unsigned og = xb_add(&bar[XB_TOP], 1u);
;             const unsigned tg = og / nx;
;             if (og + 1u == (tg + 1u) * nx) xb_add(&bar[XB_TOPGEN], 1u);
;             else XB_SPIN(xb_ld(&bar[XB_TOPGEN]) == tg, bar);
;             __builtin_amdgcn_fence(__ATOMIC_ACQUIRE, "agent");
;             xb_add(&bar[XB_XGEN(b.x)], 1u);
;             asm volatile("s_waitcnt vmcnt(0)" ::: "memory");
.LBB0_598:
	s_or_b64 exec, exec, s[8:9]
	s_mov_b64 s[8:9], exec
	v_mbcnt_lo_u32_b32 v0, s8, 0
	v_mbcnt_hi_u32_b32 v0, s9, v0
	v_cmp_eq_u32_e32 vcc, 0, v0
	s_waitcnt vmcnt(0)
	s_and_saveexec_b64 s[10:11], vcc
	s_cbranch_execz .LBB0_600
	s_bcnt1_i32_b64 s8, s[8:9]
	v_mov_b32_e32 v0, 0x2000
	v_mov_b32_e32 v1, s8
	global_atomic_add v0, v1, s[4:5] offset:1024

; __device__ __forceinline__ unsigned xb_ld(unsigned* p)              { return __hip_atomic_load(p, __ATOMIC_RELAXED, __HIP_MEMORY_SCOPE_AGENT); }
; __device__ __forceinline__ unsigned xb_add(unsigned* p, unsigned v) { return __hip_atomic_fetch_add(p, v, __ATOMIC_RELAXED, __HIP_MEMORY_SCOPE_AGENT); }
; #define XB_SPIN(cond, bar) do { unsigned _sp = 0; while (cond) { __builtin_amdgcn_s_sleep(1); \
;     if ((++_sp & 255u) == 0u) { if (xb_ld(&(bar)[XB_TMO])) break; if (_sp > XB_SPIN_CAP) { atomicAdd(&(bar)[XB_TMO], 1u); break; } } } } while (0)
; __device__ __forceinline__ void xcd_barrier(const XcdBarrier& b) {
;     ...
;             const unsigned og = xb_add(&bar[XB_TOP], 1u);
;             const unsigned tg = og / nx;
;             if (og + 1u == (tg + 1u) * nx) xb_add(&bar[XB_TOPGEN], 1u);
;             else XB_SPIN(xb_ld(&bar[XB_TOPGEN]) == tg, bar);
;             __builtin_amdgcn_fence(__ATOMIC_ACQUIRE, "agent");
;             xb_add(&bar[XB_XGEN(b.x)], 1u);
;             asm volatile("s_waitcnt vmcnt(0)" ::: "memory");
.LBB0_682:
	s_or_b64 exec, exec, s[10:11]
	s_mov_b64 s[10:11], exec
	v_mbcnt_lo_u32_b32 v0, s10, 0
	v_mbcnt_hi_u32_b32 v0, s11, v0
	v_cmp_eq_u32_e32 vcc, 0, v0
	s_waitcnt vmcnt(0)
	s_and_saveexec_b64 s[12:13], vcc
	s_cbranch_execz .LBB0_684
	s_bcnt1_i32_b64 s10, s[10:11]
	v_mov_b32_e32 v0, 0x2000
	v_mov_b32_e32 v1, s10
	global_atomic_add v0, v1, s[8:9] offset:1024
.LBB0_684:
	s_or_b64 exec, exec, s[12:13]
	buffer_inv sc1
	s_waitcnt vmcnt(0)

; __device__ __forceinline__ unsigned xb_ld(unsigned* p)              { return __hip_atomic_load(p, __ATOMIC_RELAXED, __HIP_MEMORY_SCOPE_AGENT); }
; __device__ __forceinline__ unsigned xb_add(unsigned* p, unsigned v) { return __hip_atomic_fetch_add(p, v, __ATOMIC_RELAXED, __HIP_MEMORY_SCOPE_AGENT); }
; #define XB_SPIN(cond, bar) do { unsigned _sp = 0; while (cond) { __builtin_amdgcn_s_sleep(1); \
;     if ((++_sp & 255u) == 0u) { if (xb_ld(&(bar)[XB_TMO])) break; if (_sp > XB_SPIN_CAP) { atomicAdd(&(bar)[XB_TMO], 1u); break; } } } } while (0)
; __device__ __forceinline__ void xcd_barrier(const XcdBarrier& b) {
;     ...
;             const unsigned og = xb_add(&bar[XB_TOP], 1u);
;             const unsigned tg = og / nx;
;             if (og + 1u == (tg + 1u) * nx) xb_add(&bar[XB_TOPGEN], 1u);
;             else XB_SPIN(xb_ld(&bar[XB_TOPGEN]) == tg, bar);
;             __builtin_amdgcn_fence(__ATOMIC_ACQUIRE, "agent");
;             xb_add(&bar[XB_XGEN(b.x)], 1u);
;             asm volatile("s_waitcnt vmcnt(0)" ::: "memory");
.LBB0_881:
	s_or_b64 exec, exec, s[8:9]
	s_mov_b64 s[8:9], exec
	v_mbcnt_lo_u32_b32 v0, s8, 0
	v_mbcnt_hi_u32_b32 v0, s9, v0
	v_cmp_eq_u32_e32 vcc, 0, v0
	s_waitcnt vmcnt(0)
	s_and_saveexec_b64 s[10:11], vcc
	s_cbranch_execz .LBB0_883
	s_bcnt1_i32_b64 s8, s[8:9]
	v_mov_b32_e32 v0, 0x2000
	v_mov_b32_e32 v1, s8
	global_atomic_add v0, v1, s[6:7] offset:1024

; __device__ __forceinline__ unsigned xb_ld(unsigned* p)              { return __hip_atomic_load(p, __ATOMIC_RELAXED, __HIP_MEMORY_SCOPE_AGENT); }
; __device__ __forceinline__ unsigned xb_add(unsigned* p, unsigned v) { return __hip_atomic_fetch_add(p, v, __ATOMIC_RELAXED, __HIP_MEMORY_SCOPE_AGENT); }
; #define XB_SPIN(cond, bar) do { unsigned _sp = 0; while (cond) { __builtin_amdgcn_s_sleep(1); \
;     if ((++_sp & 255u) == 0u) { if (xb_ld(&(bar)[XB_TMO])) break; if (_sp > XB_SPIN_CAP) { atomicAdd(&(bar)[XB_TMO], 1u); break; } } } } while (0)
; __device__ __forceinline__ void xcd_barrier(const XcdBarrier& b) {
;     ...
;             const unsigned og = xb_add(&bar[XB_TOP], 1u);
;             const unsigned tg = og / nx;
;             if (og + 1u == (tg + 1u) * nx) xb_add(&bar[XB_TOPGEN], 1u);
;             else XB_SPIN(xb_ld(&bar[XB_TOPGEN]) == tg, bar);
;             __builtin_amdgcn_fence(__ATOMIC_ACQUIRE, "agent");
;             xb_add(&bar[XB_XGEN(b.x)], 1u);
;             asm volatile("s_waitcnt vmcnt(0)" ::: "memory");
.LBB0_957:
	s_or_b64 exec, exec, s[10:11]
	s_mov_b64 s[10:11], exec
	v_mbcnt_lo_u32_b32 v0, s10, 0
	v_mbcnt_hi_u32_b32 v0, s11, v0
	v_cmp_eq_u32_e32 vcc, 0, v0
	s_waitcnt vmcnt(0)
	s_and_saveexec_b64 s[12:13], vcc
	s_cbranch_execz .LBB0_959
	s_bcnt1_i32_b64 s10, s[10:11]
	v_mov_b32_e32 v0, 0x2000
	v_mov_b32_e32 v1, s10
	global_atomic_add v0, v1, s[6:7] offset:1024
